# combo14 + one 4-byte s_nop in the kernel prologue: the earlier edits had shifted the three GEMM main loops by 4 mod 8 bytes against the baseline's placement; this restores their byte phase
# baseline (speedup 1.0000x reference)
.LBB0_5:
	s_or_b64 exec, exec, s[8:9]
	s_cmp_ge_i32 s6, s7
	s_cbranch_scc1 .LBB0_585
	s_load_dwordx8 s[16:23], s[0:1], 0x80
	s_add_u32 s58, s4, 0x2a10000
	s_addc_u32 s59, s5, 0
	v_lshrrev_b32_e32 v1, 20, v0
	v_lshrrev_b32_e32 v0, 10, v0
	s_waitcnt lgkmcnt(0)
	s_add_u32 s8, s22, 0x4000000
	s_addc_u32 s9, s23, 0
	v_writelane_b32 v251, s8, 12
	s_lshl_b32 s33, s36, 3
	v_or_b32_e32 v0, v0, v1
	v_writelane_b32 v251, s9, 13
	s_lshl_b32 s8, s57, 3
	s_add_u32 s70, s4, 0x2a00000
	s_addc_u32 s71, s5, 0
	s_cmpk_lt_i32 s57, 0x100
	v_writelane_b32 v251, s8, 14
	s_cselect_b64 s[8:9], -1, 0
	s_add_u32 s18, s4, 0x2800000
	v_writelane_b32 v251, s8, 15
	s_addc_u32 s19, s5, 0
	v_mov_b32_e32 v157, 0
	v_writelane_b32 v251, s9, 16
	s_add_u32 s8, s4, 0x2400000
	s_addc_u32 s9, s5, 0
	v_writelane_b32 v251, s8, 17
	v_mbcnt_lo_u32_b32 v1, -1, 0
	v_mbcnt_hi_u32_b32 v185, -1, v1
	v_writelane_b32 v251, s9, 18
	s_add_u32 s8, s4, 0x2000000
	s_addc_u32 s9, s5, 0
	v_writelane_b32 v251, s8, 19
	s_lshl_b32 s72, s36, 9
	v_and_b32_e32 v186, 64, v185
	v_writelane_b32 v251, s9, 20
	s_lshl_b32 s8, s57, 9
	s_cmpk_lt_i32 s57, 0x7a0
	v_writelane_b32 v251, s8, 21
	s_cselect_b64 s[8:9], -1, 0
	v_writelane_b32 v251, s8, 22
	s_ashr_i32 s69, s57, 31
	v_mov_b32_e32 v182, 0x358637bd
	v_writelane_b32 v251, s9, 23
	s_lshr_b32 s8, s69, 29
	s_add_i32 s9, s57, s8
	s_ashr_i32 s8, s9, 3
	s_and_b32 s9, s9, -8
	s_sub_i32 s9, s57, s9
	s_add_u32 s74, s4, 0x11c00000
	s_addc_u32 s75, s5, 0
	s_add_u32 s10, s4, 0xdc00000
	s_addc_u32 s11, s5, 0
	s_add_u32 s76, s4, 0x6c00000
	s_addc_u32 s77, s5, 0
	s_add_u32 s78, s4, 0x15500000
	s_addc_u32 s79, s5, 0
	s_ashr_i32 s80, s36, 31
	s_add_u32 s26, s4, 0x1b000000
	s_addc_u32 s27, s5, 0
	v_writelane_b32 v251, s10, 24
	s_cmpk_eq_i32 s36, 0x100
	v_mov_b32_e32 v183, 0x3ecc95a3
	v_writelane_b32 v251, s11, 25
	s_cselect_b64 s[10:11], -1, 0
	v_writelane_b32 v251, s10, 26
	v_add_u32_e32 v187, 64, v186
	v_xor_b32_e32 v188, 1, v185
	v_writelane_b32 v251, s11, 27
	s_and_b64 s[10:11], s[10:11], exec
	s_cselect_b32 s81, 0x500, s33
	s_add_u32 s10, s4, 0x1a800000
	s_addc_u32 s11, s5, 0
	v_writelane_b32 v251, s10, 28
	v_xor_b32_e32 v189, 2, v185
	v_xor_b32_e32 v190, 4, v185
	v_writelane_b32 v251, s11, 29
	s_add_u32 s10, s4, 0x19700000
	s_addc_u32 s11, s5, 0
	v_writelane_b32 v251, s10, 30
	v_xor_b32_e32 v191, 8, v185
	v_xor_b32_e32 v250, 16, v185
	v_writelane_b32 v251, s11, 31
	s_add_u32 s10, s4, 0x19f00000
	s_addc_u32 s11, s5, 0
	s_add_u32 s82, s4, 0x17600000
	s_addc_u32 s83, s5, 0
	s_add_u32 s60, s4, 0x2c00000
	s_addc_u32 s61, s5, 0
	s_add_u32 s62, s4, 0x13400000
	s_addc_u32 s63, s5, 0
	s_add_u32 s64, s4, 0x14400000
	s_addc_u32 s65, s5, 0
	s_add_u32 s66, s4, 0x12400000
	s_addc_u32 s67, s5, 0
	s_ashr_i32 s17, s36, 1
	v_writelane_b32 v251, s10, 32
	s_cmp_lt_i32 s57, s17
	v_xor_b32_e32 v184, 32, v185
	v_writelane_b32 v251, s11, 33
	s_cselect_b64 s[10:11], -1, 0
	v_writelane_b32 v251, s10, 34
	v_bfrev_b32_e32 v194, 0.5
	v_mov_b32_e32 v195, 0x7f800000
	v_writelane_b32 v251, s11, 35
	s_and_b64 s[10:11], s[10:11], exec
	s_mov_b32 s11, 0x1b400000
	s_cselect_b32 s13, s11, 0x1d400000
	s_brev_b32 s11, 64
	s_mov_b32 s10, 0x2c00000
	s_cselect_b32 s14, s11, 0x2400000
	s_cselect_b32 s11, 0, s17
	s_cselect_b32 s15, 11, 10
	s_cselect_b32 s10, s10, 0x3c00000
	v_writelane_b32 v251, s15, 36
	s_cselect_b32 s15, 0, 0x800
	s_sub_i32 s16, s57, s11
	s_cmp_lt_i32 s16, s17
	s_cselect_b64 s[20:21], -1, 0
	v_writelane_b32 v251, s20, 37
	v_mov_b32_e32 v196, 0x7fc00000
	v_mov_b32_e32 v197, 0xff800000
	v_writelane_b32 v251, s21, 38
	s_add_u32 s20, s4, s10
	s_addc_u32 s21, s5, 0
	s_cmpk_lt_i32 s16, 0x80
	s_cselect_b64 s[10:11], -1, 0
	v_writelane_b32 v251, s10, 39
	v_mov_b32_e32 v198, 0x19b30
	v_mov_b32_e32 v199, 16
	v_writelane_b32 v251, s11, 40
	s_ashr_i32 s10, s16, 31
	v_writelane_b32 v251, s10, 41
	s_lshr_b32 s10, s10, 29
	s_add_i32 s11, s16, s10
	s_ashr_i32 s10, s11, 3
	s_and_b32 s11, s11, -8
	v_writelane_b32 v251, s16, 42
	s_sub_i32 s16, s16, s11
	s_lshl_b32 s11, s16, 4
	v_writelane_b32 v251, s17, 43
	s_ashr_i32 s17, s17, 31
	v_writelane_b32 v251, s17, 44
	s_add_u32 s17, s4, s13
	s_addc_u32 s22, s5, 0
	s_add_u32 s23, s4, s14
	s_addc_u32 s24, s5, 0
	s_add_u32 s13, s4, s15
	s_addc_u32 s14, s5, 0
	s_add_u32 s28, s13, 0xfc00000
	s_addc_u32 s29, s14, 0
	v_writelane_b32 v251, s28, 45
	s_cmpk_lt_i32 s57, 0x600
	s_cselect_b64 s[14:15], -1, 0
	v_writelane_b32 v251, s29, 46
	v_writelane_b32 v251, s14, 47
	v_mov_b32_e32 v200, 0x204000
	v_mov_b32_e32 v201, 0x408000
	v_writelane_b32 v251, s15, 48
	s_add_u32 s14, s4, 0x7c00000
	s_addc_u32 s15, s5, 0
	v_writelane_b32 v251, s14, 49
	v_mov_b64_e32 v[162:163], 0x7a0
	v_mov_b64_e32 v[164:165], 0x79f
	v_writelane_b32 v251, s15, 50
	s_add_u32 s14, s4, 0x1d400000
	s_addc_u32 s15, s5, 0
	v_writelane_b32 v251, s14, 51
	v_mov_b32_e32 v202, 0xfffffec0
	s_mov_b32 s56, 0x800000
	v_writelane_b32 v251, s15, 52
	s_add_u32 s14, s4, 0x9c00000
	s_addc_u32 s15, s5, 0
	v_writelane_b32 v251, s14, 53
	s_movk_i32 s68, 0x2040
	s_movk_i32 s55, 0xfff
	v_writelane_b32 v251, s15, 54
	s_add_u32 s14, s4, 0x2a44000
	s_addc_u32 s15, s5, 0
	v_writelane_b32 v251, s14, 55
	s_mov_b32 s54, 0xf0c0
	s_mov_b64 s[30:31], 0x80
	v_writelane_b32 v251, s15, 56
	s_add_u32 s14, s4, 0x1b400000
	s_addc_u32 s15, s5, 0
	v_writelane_b32 v251, s14, 57
	s_nop 1
	v_writelane_b32 v251, s15, 58
	s_add_u32 s14, s4, 0x2a24000
	s_addc_u32 s15, s5, 0
	v_writelane_b32 v251, s14, 59
	s_nop 1
	v_writelane_b32 v251, s15, 60
	s_add_u32 s14, s4, 0x4c00000
	s_addc_u32 s15, s5, 0
	v_writelane_b32 v251, s14, 61
	s_cmpk_lt_i32 s57, 0x200
	s_nop 0
	v_writelane_b32 v251, s15, 62
	s_cselect_b64 s[14:15], -1, 0
	v_writelane_b32 v251, s14, 63
	s_nop 1
	v_writelane_b32 v252, s15, 0
	s_add_u32 s14, s4, 0x1b300000
	s_addc_u32 s15, s5, 0
	v_writelane_b32 v252, s14, 1
	s_add_u32 s13, s4, 0x1b0c0000
	s_nop 0
	v_writelane_b32 v252, s15, 2
	v_writelane_b32 v252, s13, 3
	s_addc_u32 s13, s5, 0
	s_cmp_gt_i32 s6, -1
	v_writelane_b32 v252, s13, 4
	s_cselect_b64 s[14:15], -1, 0
	v_writelane_b32 v252, s14, 5
	s_nop 1
	v_writelane_b32 v252, s15, 6
	s_add_u32 s14, s4, 0x2b00200
	s_addc_u32 s15, s5, 0
	v_writelane_b32 v252, s14, 7
	s_nop 1
	v_writelane_b32 v252, s15, 8
	s_add_u32 s14, s4, 0x2b00400
	s_addc_u32 s15, s5, 0
	v_writelane_b32 v252, s14, 9
	s_nop 1
	v_writelane_b32 v252, s15, 10
	s_add_u32 s14, s4, 0x2b00500
	s_addc_u32 s15, s5, 0
	v_writelane_b32 v252, s14, 11
	s_nop 1
	v_writelane_b32 v252, s15, 12
	s_add_u32 s14, s4, 0x2b00600
	s_addc_u32 s15, s5, 0
	v_writelane_b32 v252, s14, 13
	s_nop 1
	v_writelane_b32 v252, s15, 14
	s_add_u32 s14, s4, 0x2b00700
	s_addc_u32 s15, s5, 0
	v_writelane_b32 v252, s14, 15
	s_nop 1
	v_writelane_b32 v252, s15, 16
	s_add_u32 s14, s4, 0x2b00800
	s_addc_u32 s15, s5, 0
	v_writelane_b32 v252, s14, 17
	s_nop 1
	v_writelane_b32 v252, s15, 18
	s_add_u32 s14, s4, 0x2b00900
	s_addc_u32 s15, s5, 0
	v_writelane_b32 v252, s14, 19
	s_nop 1
	v_writelane_b32 v252, s15, 20
	s_add_u32 s14, s4, 0x2b00a00
	s_addc_u32 s15, s5, 0
	v_writelane_b32 v252, s14, 21
	s_nop 1
	v_writelane_b32 v252, s15, 22
	s_add_u32 s14, s4, 0x2b00b00
	s_addc_u32 s15, s5, 0
	v_writelane_b32 v252, s14, 23
	s_nop 1
	v_writelane_b32 v252, s15, 24
	s_add_u32 s14, s4, 0x2b00c00
	s_addc_u32 s15, s5, 0
	v_writelane_b32 v252, s14, 25
	s_nop 1
	v_writelane_b32 v252, s15, 26
	s_add_u32 s14, s4, 0x2b00d00
	s_addc_u32 s15, s5, 0
	v_writelane_b32 v252, s14, 27
	s_nop 1
	v_writelane_b32 v252, s15, 28
	s_add_u32 s14, s4, 0x2b00e00
	s_addc_u32 s15, s5, 0
	v_writelane_b32 v252, s14, 29
	s_nop 1
	v_writelane_b32 v252, s15, 30
	s_add_u32 s14, s4, 0x2b00f00
	s_addc_u32 s15, s5, 0
	v_writelane_b32 v252, s14, 31
	s_nop 1
	v_writelane_b32 v252, s15, 32
	s_add_u32 s14, s4, 0x2b01000
	s_addc_u32 s15, s5, 0
	v_writelane_b32 v252, s14, 33
	s_nop 1
	v_writelane_b32 v252, s15, 34
	s_add_u32 s14, s4, 0x2b01100
	s_addc_u32 s15, s5, 0
	v_writelane_b32 v252, s14, 35
	s_nop 1
	v_writelane_b32 v252, s15, 36
	s_add_u32 s14, s4, 0x2b01200
	s_addc_u32 s15, s5, 0
	v_writelane_b32 v252, s14, 37
	s_nop 1
	v_writelane_b32 v252, s15, 38
	s_add_u32 s14, s4, 0x2b01300
	s_addc_u32 s15, s5, 0
	v_writelane_b32 v252, s14, 39
	s_cmp_eq_u32 s12, 15
	s_nop 0
	v_writelane_b32 v252, s15, 40
	s_cselect_b64 s[14:15], -1, 0
	v_writelane_b32 v252, s14, 41
	s_cmp_eq_u32 s12, 14
	s_nop 0
	v_writelane_b32 v252, s15, 42
	s_cselect_b64 s[14:15], -1, 0
	v_writelane_b32 v252, s14, 43
	s_cmp_eq_u32 s12, 13
	s_nop 0
	v_writelane_b32 v252, s15, 44
	s_cselect_b64 s[14:15], -1, 0
	v_writelane_b32 v252, s14, 45
	s_cmp_eq_u32 s12, 12
	s_nop 0
	v_writelane_b32 v252, s15, 46
	s_cselect_b64 s[14:15], -1, 0
	v_writelane_b32 v252, s14, 47
	s_cmp_eq_u32 s12, 11
	s_nop 0
	v_writelane_b32 v252, s15, 48
	s_cselect_b64 s[14:15], -1, 0
	v_writelane_b32 v252, s14, 49
	s_cmp_eq_u32 s12, 10
	s_nop 0
	v_writelane_b32 v252, s15, 50
	s_cselect_b64 s[14:15], -1, 0
	v_writelane_b32 v252, s14, 51
	s_cmp_eq_u32 s12, 9
	s_nop 0
	v_writelane_b32 v252, s15, 52
	s_cselect_b64 s[14:15], -1, 0
	v_writelane_b32 v252, s14, 53
	s_cmp_eq_u32 s12, 8
	s_nop 0
	v_writelane_b32 v252, s15, 54
	s_cselect_b64 s[14:15], -1, 0
	v_writelane_b32 v252, s14, 55
	s_cmp_eq_u32 s12, 7
	s_nop 0
	v_writelane_b32 v252, s15, 56
	s_cselect_b64 s[14:15], -1, 0
	v_writelane_b32 v252, s14, 57
	s_cmp_eq_u32 s12, 6
	s_nop 0
	v_writelane_b32 v252, s15, 58
	s_cselect_b64 s[14:15], -1, 0
	v_writelane_b32 v252, s14, 59
	s_cmp_eq_u32 s12, 5
	s_nop 0
	v_writelane_b32 v252, s15, 60
	s_cselect_b64 s[14:15], -1, 0
	v_writelane_b32 v252, s14, 61
	s_cmp_eq_u32 s12, 4
	s_nop 0
	v_writelane_b32 v252, s15, 62
	s_cselect_b64 s[14:15], -1, 0
	v_writelane_b32 v252, s14, 63
	s_cmp_eq_u32 s12, 3
	s_nop 0
	v_writelane_b32 v253, s15, 0
	s_cselect_b64 s[14:15], -1, 0
	v_writelane_b32 v253, s14, 1
	s_cmp_eq_u32 s12, 2
	s_nop 0
	v_writelane_b32 v253, s15, 2
	s_cselect_b64 s[14:15], -1, 0
	v_writelane_b32 v253, s14, 3
	s_cmp_eq_u32 s12, 1
	s_nop 0
	v_writelane_b32 v253, s15, 4
	s_cselect_b64 s[14:15], -1, 0
	v_writelane_b32 v253, s14, 5
	s_cmp_eq_u32 s12, 0
	s_nop 0
	v_writelane_b32 v253, s15, 6
	s_cselect_b64 s[14:15], -1, 0
	s_lshl_b32 s12, s12, 8
	s_add_u32 s2, s2, s12
	s_addc_u32 s3, s3, 0
	v_writelane_b32 v253, s14, 7
	s_add_u32 s12, s2, 0x1400
	s_addc_u32 s13, s3, 0
	v_writelane_b32 v253, s15, 8
	v_writelane_b32 v253, s12, 9
	s_add_u32 s2, s2, 0x2400
	s_addc_u32 s3, s3, 0
	v_writelane_b32 v253, s13, 10
	v_writelane_b32 v253, s2, 11
	s_nop 1
	v_writelane_b32 v253, s3, 12
	s_add_u32 s2, s4, 0x2b03400
	s_addc_u32 s3, s5, 0
	v_writelane_b32 v253, s2, 13
	s_nop 1
	v_writelane_b32 v253, s3, 14
	s_add_u32 s2, s4, 0x2b03500
	s_addc_u32 s3, s5, 0
	v_writelane_b32 v253, s2, 15
	s_cmp_lt_i32 s9, 0
	s_nop 0
	v_writelane_b32 v253, s3, 16
	s_movk_i32 s2, 0xf5
	s_cselect_b32 s2, s2, 0xf4
	s_mul_i32 s2, s9, s2
	s_add_i32 s2, s2, s8
	s_mul_hi_i32 s3, s2, 0x4325c53f
	s_lshr_b32 s8, s3, 31
	s_ashr_i32 s3, s3, 7
	s_add_i32 s3, s3, s8
	s_mul_i32 s8, s3, 0x1e8
	s_sub_i32 s2, s2, s8
	s_bfe_u32 s8, s2, 0x3001c
	s_add_i32 s8, s2, s8
	s_and_b32 s9, s8, 0xfff8
	s_sub_i32 s2, s2, s9
	s_lshl_b32 s3, s3, 3
	s_sext_i32_i16 s8, s8
	s_sext_i32_i16 s2, s2
	s_add_i32 s14, s3, s2
	s_ashr_i32 s2, s8, 3
	v_writelane_b32 v253, s2, 17
	s_lshr_b32 s2, s8, 3
	s_cmp_lt_i32 s16, 0
	s_mul_i32 s16, s16, 17
	s_cselect_b32 s3, s16, s11
	s_add_i32 s3, s3, s10
	s_ashr_i32 s8, s3, 31
	s_lshr_b32 s8, s8, 27
	s_add_i32 s8, s3, s8
	s_and_b32 s9, s8, 0xffe0
	s_sub_i32 s3, s3, s9
	s_bfe_i32 s9, s3, 0x80000
	s_bfe_u32 s9, s9, 0x3000c
	s_add_i32 s9, s3, s9
	s_and_b32 s10, s9, 0xf8
	s_sub_i32 s3, s3, s10
	s_ashr_i32 s8, s8, 5
	s_bfe_i32 s9, s9, 0x80000
	s_lshl_b32 s8, s8, 3
	s_sext_i32_i16 s9, s9
	s_sext_i32_i8 s3, s3
	s_add_i32 s28, s8, s3
	s_lshr_b32 s8, s9, 3
	s_ashr_i32 s29, s28, 31
	s_ashr_i32 s3, s9, 3
	s_bfe_i64 s[8:9], s[8:9], 0x100000
	s_lshl_b64 s[10:11], s[28:29], 19
	s_lshl_b64 s[12:13], s[8:9], 19
	v_writelane_b32 v253, s3, 18
	s_add_u32 s12, s18, s12
	v_writelane_b32 v253, s18, 19
	s_addc_u32 s13, s19, s13
	s_nop 0
	v_writelane_b32 v253, s19, 20
	s_add_u32 s18, s12, 0x40000
	s_addc_u32 s19, s13, 0
	v_writelane_b32 v253, s18, 21
	s_add_u32 s10, s20, s10
	s_nop 0
	v_writelane_b32 v253, s19, 22
	v_writelane_b32 v253, s20, 23
	s_addc_u32 s11, s21, s11
	s_add_u32 s18, s10, 0x40000
	v_writelane_b32 v253, s21, 24
	v_writelane_b32 v253, s10, 25
	s_addc_u32 s19, s11, 0
	s_nop 0
	v_writelane_b32 v253, s11, 26
	v_writelane_b32 v253, s18, 27
	s_add_u32 s10, s12, 0x40080
	s_nop 0
	v_writelane_b32 v253, s19, 28
	v_writelane_b32 v253, s12, 29
	s_addc_u32 s11, s13, 0
	s_lshl_b64 s[8:9], s[8:9], 20
	v_writelane_b32 v253, s13, 30
	v_writelane_b32 v253, s10, 31
	s_nop 1
	v_writelane_b32 v253, s11, 32
	s_mov_b32 s10, s28
	v_writelane_b32 v253, s10, 33
	s_nop 1
	v_writelane_b32 v253, s11, 34
	s_lshl_b64 s[10:11], s[28:29], 20
	s_add_u32 s8, s23, s8
	s_addc_u32 s9, s24, s9
	v_writelane_b32 v253, s23, 35
	s_add_u32 s12, s8, 0x80000
	v_writelane_b32 v253, s24, 36
	s_addc_u32 s13, s9, 0
	v_writelane_b32 v253, s12, 37
	s_add_u32 s10, s17, s10
	s_addc_u32 s11, s22, s11
	v_writelane_b32 v253, s13, 38
	v_writelane_b32 v253, s17, 39
	v_writelane_b32 v253, s22, 40
	s_add_u32 s12, s10, 0x80000
	v_writelane_b32 v253, s10, 41
	s_addc_u32 s13, s11, 0
	s_mov_b32 s29, 0
	v_writelane_b32 v253, s11, 42
	v_writelane_b32 v253, s12, 43
	s_add_u32 s10, s8, 0x80080
	s_nop 0
	v_writelane_b32 v253, s13, 44
	v_writelane_b32 v253, s8, 45
	s_addc_u32 s11, s9, 0
	s_ashr_i32 s15, s14, 31
	v_writelane_b32 v253, s9, 46
	v_writelane_b32 v253, s10, 47
	s_mov_b32 s8, s14
	s_bfe_i64 s[2:3], s[2:3], 0x100000
	v_writelane_b32 v253, s11, 48
	v_writelane_b32 v253, s8, 49
	s_lshl_b64 s[2:3], s[2:3], 19
	s_nop 0
	v_writelane_b32 v253, s9, 50
	s_lshl_b64 s[8:9], s[14:15], 19
	v_writelane_b32 v253, s8, 51
	s_nop 1
	v_writelane_b32 v253, s9, 52
	s_add_u32 s8, s4, s2
	s_addc_u32 s9, s5, s3
	s_load_dword s3, s[0:1], 0xb8
	s_mul_i32 s2, s37, s36
	s_movk_i32 s37, 0x4080
	s_waitcnt lgkmcnt(0)
	s_mul_i32 s2, s2, s3
	v_writelane_b32 v253, s2, 53
	s_movk_i32 s2, 0x3ff
	v_and_or_b32 v0, v0, s2, v167
	s_add_u32 s2, s8, 0x40000
	s_addc_u32 s3, s9, 0
	v_writelane_b32 v253, s2, 54
	s_nop 1
	v_writelane_b32 v253, s3, 55
	s_add_u32 s2, s8, 0x40080
	v_writelane_b32 v253, s8, 56
	s_addc_u32 s3, s9, 0
	s_ashr_i32 s73, s72, 31
	v_writelane_b32 v253, s9, 57
	v_writelane_b32 v253, s2, 58
	s_load_dwordx16 s[8:23], s[0:1], 0x0
	s_nop 0
	v_writelane_b32 v253, s3, 59
	s_add_i32 s2, s57, 0xfffffc00
	v_writelane_b32 v253, s2, 60
	s_add_i32 s2, s57, 0xffffff00
	v_writelane_b32 v253, s2, 61
	s_add_i32 s2, 16, 0x10c00
	v_writelane_b32 v253, s2, 62
	s_add_i32 s2, 16, 0x1b000
	v_writelane_b32 v253, s2, 63
	v_cmp_eq_u32_e64 s[2:3], 0, v0
	s_nop 1
	v_writelane_b32 v254, s2, 0
	s_nop 1
	v_writelane_b32 v254, s3, 1
	s_lshl_b64 s[2:3], s[72:73], 2
	v_writelane_b32 v254, s2, 2
	s_movk_i32 s73, 0xf5
	s_nop 0
	v_writelane_b32 v254, s3, 3
	s_waitcnt lgkmcnt(0)
	v_writelane_b32 v254, s8, 4
	s_mov_b64 s[2:3], 0x300000
	s_nop 0
	v_writelane_b32 v254, s9, 5
	v_writelane_b32 v254, s10, 6
	v_writelane_b32 v254, s11, 7
	v_writelane_b32 v254, s12, 8
	v_writelane_b32 v254, s13, 9
	v_writelane_b32 v254, s14, 10
	v_writelane_b32 v254, s15, 11
	v_writelane_b32 v254, s16, 12
	v_writelane_b32 v254, s17, 13
	v_writelane_b32 v254, s18, 14
	v_writelane_b32 v254, s19, 15
	v_writelane_b32 v254, s20, 16
	v_writelane_b32 v254, s21, 17
	v_writelane_b32 v254, s22, 18
	v_writelane_b32 v254, s23, 19
	s_load_dwordx16 s[8:23], s[0:1], 0x40
	s_waitcnt lgkmcnt(0)
	v_writelane_b32 v254, s8, 20
	s_nop 1
	v_writelane_b32 v254, s9, 21
	v_writelane_b32 v254, s10, 22
	v_writelane_b32 v254, s11, 23
	v_writelane_b32 v254, s12, 24
	v_writelane_b32 v254, s13, 25
	v_writelane_b32 v254, s14, 26
	v_writelane_b32 v254, s15, 27
	v_writelane_b32 v254, s16, 28
	v_writelane_b32 v254, s17, 29
	v_writelane_b32 v254, s18, 30
	v_writelane_b32 v254, s19, 31
	v_writelane_b32 v254, s20, 32
	v_writelane_b32 v254, s21, 33
	v_writelane_b32 v254, s22, 34
	v_writelane_b32 v254, s23, 35
	v_writelane_b32 v254, s57, 36
	v_writelane_b32 v254, s58, 37
	v_writelane_b32 v254, s59, 38
	v_writelane_b32 v254, s70, 39
	s_nop 1
	v_writelane_b32 v254, s71, 40
	v_writelane_b32 v254, s72, 41
	s_nop 1
	v_writelane_b32 v254, s73, 42
	v_writelane_b32 v254, s69, 43
	v_writelane_b32 v254, s74, 44
	s_nop 1
	v_writelane_b32 v254, s75, 45
	v_writelane_b32 v254, s76, 46
	s_nop 1
	v_writelane_b32 v254, s77, 47
	v_writelane_b32 v254, s78, 48
	s_nop 1
	v_writelane_b32 v254, s79, 49
	v_writelane_b32 v254, s80, 50
	v_writelane_b32 v254, s81, 51
	v_writelane_b32 v254, s82, 52
	s_nop 1
	v_writelane_b32 v254, s83, 53
	v_writelane_b32 v254, s60, 54
	s_nop 1
	v_writelane_b32 v254, s61, 55
	v_writelane_b32 v254, s62, 56
	s_nop 1
	v_writelane_b32 v254, s63, 57
	v_writelane_b32 v254, s64, 58
	s_nop 1
	v_writelane_b32 v254, s65, 59
	v_writelane_b32 v254, s66, 60
	s_nop 1
	v_writelane_b32 v254, s67, 61
	s_nop 0
	s_branch .LBB0_11
